# phase E RKP loop: five loads per iteration issued together and prefetched one iteration ahead (was 3 dependent load rounds with vmcnt(0) each)
# speedup vs baseline: 1.0078x; 1.0031x over previous
.LBB0_764:
	s_or_b64 exec, exec, s[18:19]
	s_mov_b64 s[4:5], 0x80000
	v_lshlrev_b32_e32 v18, 2, v32
	v_cmp_gt_u64_e32 vcc, s[4:5], v[12:13]
	s_and_saveexec_b64 s[18:19], vcc
	s_cbranch_execz .LBB0_767
	s_add_u32 s20, s12, 0xf500000
	s_addc_u32 s21, s13, 0
	v_readlane_b32 s4, v252, 61
	s_add_u32 s4, s12, s4
	v_readlane_b32 s5, v252, 62
	s_addc_u32 s5, s13, s5
	s_lshl_b64 s[22:23], s[0:1], 13
	v_lshl_add_u64 v[14:15], v[8:9], 4, s[4:5]
	v_readlane_b32 s4, v252, 56
	v_readlane_b32 s5, v252, 57
	s_lshl_b64 s[24:25], s[0:1], 11
	s_mov_b64 s[26:27], 0
	v_lshl_add_u64 v[16:17], v[8:9], 2, s[4:5]
	s_mov_b64 s[6:7], 0x800000
	s_mov_b64 s[8:9], 0x1000000
	s_mov_b64 s[10:11], 0x1800000
	v_lshl_add_u64 v[142:143], v[14:15], 0, s[6:7]
	global_load_dwordx4 v[100:103], v[14:15], off
	global_load_dwordx4 v[104:107], v[142:143], off
	v_lshl_add_u64 v[144:145], v[14:15], 0, s[8:9]
	v_lshl_add_u64 v[146:147], v[14:15], 0, s[10:11]
	global_load_dwordx4 v[108:111], v[144:145], off
	global_load_dwordx4 v[112:115], v[146:147], off
	v_and_b32_e32 v19, 0xffc, v16
	v_and_b32_e32 v2, 0x7c000, v12
	v_lshl_add_u64 v[148:149], s[20:21], 0, v[2:3]
	v_lshlrev_b32_e32 v2, 2, v19
	v_lshl_add_u64 v[148:149], v[148:149], 0, v[2:3]
	global_load_dwordx4 v[116:119], v[148:149], off
.LBB0_766:
	s_waitcnt vmcnt(0)
	v_mov_b64_e32 v[120:121], v[100:101]
	v_mov_b64_e32 v[122:123], v[102:103]
	v_mov_b64_e32 v[124:125], v[104:105]
	v_mov_b64_e32 v[126:127], v[106:107]
	v_mov_b64_e32 v[128:129], v[108:109]
	v_mov_b64_e32 v[130:131], v[110:111]
	v_mov_b64_e32 v[132:133], v[112:113]
	v_mov_b64_e32 v[134:135], v[114:115]
	v_mov_b64_e32 v[136:137], v[116:117]
	v_mov_b64_e32 v[138:139], v[118:119]
	v_add_co_u32_e32 v140, vcc, 0x2bc6a000, v14
	s_nop 1
	v_addc_co_u32_e32 v141, vcc, 0, v15, vcc
	v_lshl_add_u64 v[12:13], v[12:13], 0, s[16:17]
	v_lshl_add_u64 v[16:17], v[16:17], 0, s[24:25]
	v_lshl_add_u64 v[14:15], v[14:15], 0, s[22:23]
	s_mov_b64 s[4:5], 0x7ffff
	v_cmp_ge_u64_e32 vcc, s[4:5], v[12:13]
	s_and_saveexec_b64 s[42:43], vcc
	s_cbranch_execz .Lrkp_nopf
	v_lshl_add_u64 v[142:143], v[14:15], 0, s[6:7]
	global_load_dwordx4 v[100:103], v[14:15], off
	global_load_dwordx4 v[104:107], v[142:143], off
	v_lshl_add_u64 v[144:145], v[14:15], 0, s[8:9]
	v_lshl_add_u64 v[146:147], v[14:15], 0, s[10:11]
	global_load_dwordx4 v[108:111], v[144:145], off
	global_load_dwordx4 v[112:115], v[146:147], off
	v_and_b32_e32 v19, 0xffc, v16
	v_and_b32_e32 v2, 0x7c000, v12
	v_lshl_add_u64 v[148:149], s[20:21], 0, v[2:3]
	v_lshlrev_b32_e32 v2, 2, v19
	v_lshl_add_u64 v[148:149], v[148:149], 0, v[2:3]
	global_load_dwordx4 v[116:119], v[148:149], off
.Lrkp_nopf:
	s_mov_b64 exec, s[42:43]
	v_pk_add_f32 v[26:27], v[120:121], v[124:125]
	v_pk_add_f32 v[24:25], v[122:123], v[126:127]
	v_pk_add_f32 v[8:9], v[128:129], v[132:133]
	v_pk_add_f32 v[10:11], v[130:131], v[134:135]
	v_pk_add_f32 v[22:23], v[26:27], v[8:9]
	v_pk_add_f32 v[20:21], v[24:25], v[10:11]
	v_pk_add_f32 v[8:9], v[136:137], v[22:23]
	s_nop 0
	v_fmamk_f32 v2, v8, 0x3baaaaab, v201
	v_cmp_gt_f32_e32 vcc, s91, v2
	v_mul_f32_e32 v8, 0x4f800000, v2
	v_pk_add_f32 v[10:11], v[138:139], v[20:21]
	v_cndmask_b32_e32 v2, v2, v8, vcc
	v_sqrt_f32_e32 v8, v2
	s_nop 0
	v_add_u32_e32 v19, -1, v8
	v_fma_f32 v20, -v19, v8, v2
	v_cmp_ge_f32_e64 s[42:43], 0, v20
	v_add_u32_e32 v20, 1, v8
	s_nop 0
	v_cndmask_b32_e64 v19, v8, v19, s[42:43]
	v_fma_f32 v8, -v20, v8, v2
	v_cmp_lt_f32_e64 s[42:43], 0, v8
	s_nop 1
	v_cndmask_b32_e64 v8, v19, v20, s[42:43]
	v_mul_f32_e32 v19, 0x37800000, v8
	v_cndmask_b32_e32 v8, v8, v19, vcc
	v_cmp_class_f32_e32 vcc, v2, v202
	s_nop 1
	v_cndmask_b32_e32 v2, v8, v2, vcc
	v_div_scale_f32 v8, s[4:5], v2, v2, 1.0
	v_rcp_f32_e32 v19, v8
	s_nop 0
	v_fma_f32 v20, -v8, v19, 1.0
	v_fmac_f32_e32 v19, v20, v19
	v_div_scale_f32 v20, vcc, 1.0, v2, 1.0
	v_mul_f32_e32 v21, v20, v19
	v_fma_f32 v22, -v8, v21, v20
	v_fmac_f32_e32 v21, v22, v19
	v_fma_f32 v8, -v8, v21, v20
	v_div_fmas_f32 v8, v8, v19, v21
	v_div_fixup_f32 v8, v8, v2, 1.0
	v_fmamk_f32 v2, v9, 0x3baaaaab, v201
	v_cmp_gt_f32_e32 vcc, s91, v2
	v_mul_f32_e32 v9, 0x4f800000, v2
	s_nop 0
	v_cndmask_b32_e32 v2, v2, v9, vcc
	v_sqrt_f32_e32 v9, v2
	s_nop 0
	v_add_u32_e32 v19, -1, v9
	v_fma_f32 v20, -v19, v9, v2
	v_cmp_ge_f32_e64 s[42:43], 0, v20
	v_add_u32_e32 v20, 1, v9
	s_nop 0
	v_cndmask_b32_e64 v19, v9, v19, s[42:43]
	v_fma_f32 v9, -v20, v9, v2
	v_cmp_lt_f32_e64 s[42:43], 0, v9
	s_nop 1
	v_cndmask_b32_e64 v9, v19, v20, s[42:43]
	v_mul_f32_e32 v19, 0x37800000, v9
	v_cndmask_b32_e32 v9, v9, v19, vcc
	v_cmp_class_f32_e32 vcc, v2, v202
	s_nop 1
	v_cndmask_b32_e32 v2, v9, v2, vcc
	v_div_scale_f32 v9, s[4:5], v2, v2, 1.0
	v_rcp_f32_e32 v19, v9
	s_nop 0
	v_fma_f32 v20, -v9, v19, 1.0
	v_fmac_f32_e32 v19, v20, v19
	v_div_scale_f32 v20, vcc, 1.0, v2, 1.0
	v_mul_f32_e32 v21, v20, v19
	v_fma_f32 v22, -v9, v21, v20
	v_fmac_f32_e32 v21, v22, v19
	v_fma_f32 v9, -v9, v21, v20
	v_div_fmas_f32 v9, v9, v19, v21
	v_div_fixup_f32 v9, v9, v2, 1.0
	v_fmamk_f32 v2, v10, 0x3baaaaab, v201
	v_cmp_gt_f32_e32 vcc, s91, v2
	v_mul_f32_e32 v10, 0x4f800000, v2
	s_nop 0
	v_cndmask_b32_e32 v2, v2, v10, vcc
	v_sqrt_f32_e32 v10, v2
	s_nop 0
	v_add_u32_e32 v19, -1, v10
	v_fma_f32 v20, -v19, v10, v2
	v_cmp_ge_f32_e64 s[42:43], 0, v20
	v_add_u32_e32 v20, 1, v10
	s_nop 0
	v_cndmask_b32_e64 v19, v10, v19, s[42:43]
	v_fma_f32 v10, -v20, v10, v2
	v_cmp_lt_f32_e64 s[42:43], 0, v10
	s_nop 1
	v_cndmask_b32_e64 v10, v19, v20, s[42:43]
	v_mul_f32_e32 v19, 0x37800000, v10
	v_cndmask_b32_e32 v10, v10, v19, vcc
	v_cmp_class_f32_e32 vcc, v2, v202
	s_nop 1
	v_cndmask_b32_e32 v2, v10, v2, vcc
	v_div_scale_f32 v10, s[4:5], v2, v2, 1.0
	v_rcp_f32_e32 v19, v10
	s_nop 0
	v_fma_f32 v20, -v10, v19, 1.0
	v_fmac_f32_e32 v19, v20, v19
	v_div_scale_f32 v20, vcc, 1.0, v2, 1.0
	v_mul_f32_e32 v21, v20, v19
	v_fma_f32 v22, -v10, v21, v20
	v_fmac_f32_e32 v21, v22, v19
	v_fma_f32 v10, -v10, v21, v20
	v_div_fmas_f32 v10, v10, v19, v21
	v_div_fixup_f32 v10, v10, v2, 1.0
	v_fmamk_f32 v2, v11, 0x3baaaaab, v201
	v_cmp_gt_f32_e32 vcc, s91, v2
	v_mul_f32_e32 v11, 0x4f800000, v2
	s_nop 0
	v_cndmask_b32_e32 v2, v2, v11, vcc
	v_sqrt_f32_e32 v11, v2
	s_nop 0
	v_add_u32_e32 v19, -1, v11
	v_fma_f32 v20, -v19, v11, v2
	v_cmp_ge_f32_e64 s[42:43], 0, v20
	v_add_u32_e32 v20, 1, v11
	s_nop 0
	v_cndmask_b32_e64 v19, v11, v19, s[42:43]
	v_fma_f32 v11, -v20, v11, v2
	v_cmp_lt_f32_e64 s[42:43], 0, v11
	s_nop 1
	v_cndmask_b32_e64 v11, v19, v20, s[42:43]
	v_mul_f32_e32 v19, 0x37800000, v11
	v_cndmask_b32_e32 v11, v11, v19, vcc
	v_cmp_class_f32_e32 vcc, v2, v202
	s_nop 1
	v_cndmask_b32_e32 v2, v11, v2, vcc
	v_div_scale_f32 v11, s[4:5], v2, v2, 1.0
	v_rcp_f32_e32 v19, v11
	s_mov_b64 s[4:5], 0x7ffff
	v_fma_f32 v20, -v11, v19, 1.0
	v_fmac_f32_e32 v19, v20, v19
	v_div_scale_f32 v20, vcc, 1.0, v2, 1.0
	v_mul_f32_e32 v21, v20, v19
	v_fma_f32 v22, -v11, v21, v20
	v_fmac_f32_e32 v21, v22, v19
	v_fma_f32 v11, -v11, v21, v20
	v_div_fmas_f32 v11, v11, v19, v21
	v_div_fixup_f32 v11, v11, v2, 1.0
	s_nop 0
	v_cmp_lt_u64_e32 vcc, s[4:5], v[12:13]
	s_or_b64 s[26:27], vcc, s[26:27]
	global_store_dwordx4 v[140:141], v[8:11], off
	s_andn2_b64 exec, exec, s[26:27]
	s_cbranch_execnz .LBB0_766
